# v4 + first LDS read of a freshly filled stage delayed past 8 MFMAs + latent attention QK phase re-scheduled (K fragments read 4-5 ahead into rotating buffers)
# speedup vs baseline: 1.0550x; 1.0037x over previous
.LBB0_167:
	s_lshl_b32 s7, s45, 7
	s_add_u32 s14, s2, s7
	s_addc_u32 s15, s3, 0
	s_add_u32 s12, s0, s7
	s_addc_u32 s13, s1, 0
	v_readfirstlane_b32 s16, v147
	v_add_u32_e32 v0, v158, v159
	v_add_u32_e32 v177, v146, v160
	s_mov_b32 m0, s16
	s_cmp_eq_u32 s46, 0
	s_cbranch_scc1 .Lp2_first
	v_mfma_f32_16x16x32_bf16 v[122:125], v[242:245], v[178:181], v[122:125]
	global_load_lds_dwordx4 v130, s[14:15]
	s_add_u32 m0, m0, 0x2000
	v_mfma_f32_16x16x32_bf16 v[106:109], v[242:245], v[182:185], v[106:109]
	v_mfma_f32_16x16x32_bf16 v[90:93], v[242:245], v[186:189], v[90:93]
	v_mfma_f32_16x16x32_bf16 v[74:77], v[242:245], v[190:193], v[74:77]
	global_load_lds_dwordx4 v132, s[14:15]
	s_add_u32 m0, m0, 0x2000
	v_mfma_f32_16x16x32_bf16 v[58:61], v[242:245], v[222:225], v[58:61]
	v_mfma_f32_16x16x32_bf16 v[42:45], v[242:245], v[226:229], v[42:45]
	v_mfma_f32_16x16x32_bf16 v[26:29], v[242:245], v[230:233], v[26:29]
	global_load_lds_dwordx4 v134, s[14:15]
	s_add_u32 m0, m0, 0x2000
	v_mfma_f32_16x16x32_bf16 v[10:13], v[242:245], v[234:237], v[10:13]
	ds_read_b128 v[238:241], v177 offset:32768
	ds_read_b128 v[242:245], v177 offset:34816
	v_mfma_f32_16x16x32_bf16 v[118:121], v[246:249], v[178:181], v[118:121]
	v_mfma_f32_16x16x32_bf16 v[114:117], v[212:215], v[178:181], v[114:117]
	global_load_lds_dwordx4 v136, s[14:15]
	s_add_u32 m0, m0, 0x2000
	ds_read_b128 v[178:181], v162
	v_mfma_f32_16x16x32_bf16 v[102:105], v[246:249], v[182:185], v[102:105]
	v_mfma_f32_16x16x32_bf16 v[98:101], v[212:215], v[182:185], v[98:101]
	ds_read_b128 v[182:185], v163
	v_mfma_f32_16x16x32_bf16 v[86:89], v[246:249], v[186:189], v[86:89]
	global_load_lds_dwordx4 v130, s[12:13]
	s_add_u32 m0, m0, 0x2000
	v_mfma_f32_16x16x32_bf16 v[82:85], v[212:215], v[186:189], v[82:85]
	ds_read_b128 v[186:189], v164
	v_mfma_f32_16x16x32_bf16 v[70:73], v[246:249], v[190:193], v[70:73]
	v_mfma_f32_16x16x32_bf16 v[66:69], v[212:215], v[190:193], v[66:69]
	global_load_lds_dwordx4 v132, s[12:13]
	s_add_u32 m0, m0, 0x2000
	ds_read_b128 v[190:193], v165
	v_mfma_f32_16x16x32_bf16 v[54:57], v[246:249], v[222:225], v[54:57]
	v_mfma_f32_16x16x32_bf16 v[50:53], v[212:215], v[222:225], v[50:53]
	ds_read_b128 v[222:225], v166
	v_mfma_f32_16x16x32_bf16 v[38:41], v[246:249], v[226:229], v[38:41]
	global_load_lds_dwordx4 v134, s[12:13]
	s_add_u32 m0, m0, 0x2000
	v_mfma_f32_16x16x32_bf16 v[34:37], v[212:215], v[226:229], v[34:37]
	ds_read_b128 v[226:229], v167
	v_mfma_f32_16x16x32_bf16 v[22:25], v[246:249], v[230:233], v[22:25]
	v_mfma_f32_16x16x32_bf16 v[18:21], v[212:215], v[230:233], v[18:21]
	global_load_lds_dwordx4 v136, s[12:13]
	ds_read_b128 v[230:233], v168
	v_mfma_f32_16x16x32_bf16 v[6:9], v[246:249], v[234:237], v[6:9]
	v_mfma_f32_16x16x32_bf16 v[2:5], v[212:215], v[234:237], v[2:5]
	ds_read_b128 v[234:237], v0
	ds_read_b128 v[246:249], v177 offset:36864
	ds_read_b128 v[212:215], v177 offset:38912
	s_add_i32 s6, s6, 1
	s_cmp_lg_u32 s6, 32
	s_cbranch_scc0 .Lp2_epi0

.Lp2_body1:
	s_lshl_b32 s7, s45, 7
	s_add_u32 s14, s2, s7
	s_addc_u32 s15, s3, 0
	s_add_u32 s12, s0, s7
	s_addc_u32 s13, s1, 0
	v_readfirstlane_b32 s16, v138
	v_add_u32_e32 v0, v161, v157
	s_mov_b32 m0, s16
	v_mfma_f32_16x16x32_bf16 v[122:125], v[242:245], v[178:181], v[122:125]
	global_load_lds_dwordx4 v130, s[14:15]
	s_add_u32 m0, m0, 0x2000
	v_mfma_f32_16x16x32_bf16 v[106:109], v[242:245], v[182:185], v[106:109]
	v_mfma_f32_16x16x32_bf16 v[90:93], v[242:245], v[186:189], v[90:93]
	v_mfma_f32_16x16x32_bf16 v[74:77], v[242:245], v[190:193], v[74:77]
	global_load_lds_dwordx4 v132, s[14:15]
	s_add_u32 m0, m0, 0x2000
	v_mfma_f32_16x16x32_bf16 v[58:61], v[242:245], v[222:225], v[58:61]
	v_mfma_f32_16x16x32_bf16 v[42:45], v[242:245], v[226:229], v[42:45]
	v_mfma_f32_16x16x32_bf16 v[26:29], v[242:245], v[230:233], v[26:29]
	global_load_lds_dwordx4 v134, s[14:15]
	s_add_u32 m0, m0, 0x2000
	v_mfma_f32_16x16x32_bf16 v[10:13], v[242:245], v[234:237], v[10:13]
	ds_read_b128 v[238:241], v176
	ds_read_b128 v[242:245], v176 offset:2048
	v_mfma_f32_16x16x32_bf16 v[118:121], v[246:249], v[178:181], v[118:121]
	v_mfma_f32_16x16x32_bf16 v[114:117], v[212:215], v[178:181], v[114:117]
	global_load_lds_dwordx4 v136, s[14:15]
	s_add_u32 m0, m0, 0x2000
	ds_read_b128 v[178:181], v169
	v_mfma_f32_16x16x32_bf16 v[102:105], v[246:249], v[182:185], v[102:105]
	v_mfma_f32_16x16x32_bf16 v[98:101], v[212:215], v[182:185], v[98:101]
	ds_read_b128 v[182:185], v0
	v_mfma_f32_16x16x32_bf16 v[86:89], v[246:249], v[186:189], v[86:89]
	global_load_lds_dwordx4 v130, s[12:13]
	s_add_u32 m0, m0, 0x2000
	v_mfma_f32_16x16x32_bf16 v[82:85], v[212:215], v[186:189], v[82:85]
	ds_read_b128 v[186:189], v170
	v_mfma_f32_16x16x32_bf16 v[70:73], v[246:249], v[190:193], v[70:73]
	v_mfma_f32_16x16x32_bf16 v[66:69], v[212:215], v[190:193], v[66:69]
	global_load_lds_dwordx4 v132, s[12:13]
	s_add_u32 m0, m0, 0x2000
	ds_read_b128 v[190:193], v171
	v_mfma_f32_16x16x32_bf16 v[54:57], v[246:249], v[222:225], v[54:57]
	v_mfma_f32_16x16x32_bf16 v[50:53], v[212:215], v[222:225], v[50:53]
	ds_read_b128 v[222:225], v172
	v_mfma_f32_16x16x32_bf16 v[38:41], v[246:249], v[226:229], v[38:41]
	global_load_lds_dwordx4 v134, s[12:13]
	s_add_u32 m0, m0, 0x2000
	v_mfma_f32_16x16x32_bf16 v[34:37], v[212:215], v[226:229], v[34:37]
	ds_read_b128 v[226:229], v173
	v_mfma_f32_16x16x32_bf16 v[22:25], v[246:249], v[230:233], v[22:25]
	v_mfma_f32_16x16x32_bf16 v[18:21], v[212:215], v[230:233], v[18:21]
	global_load_lds_dwordx4 v136, s[12:13]
	ds_read_b128 v[230:233], v174
	v_mfma_f32_16x16x32_bf16 v[6:9], v[246:249], v[234:237], v[6:9]
	v_mfma_f32_16x16x32_bf16 v[2:5], v[212:215], v[234:237], v[2:5]
	ds_read_b128 v[234:237], v175
	ds_read_b128 v[246:249], v176 offset:4096
	ds_read_b128 v[212:215], v176 offset:6144
	s_add_i32 s6, s6, 1
	s_cmp_lg_u32 s6, 32
	s_cbranch_scc0 .Lp2_epi1

.LBB0_827:
	s_bitcmp1_b32 s7, 0
	s_cselect_b32 s13, 0x8c00, 0
	v_or_b32_e32 v122, s13, v0
	v_add_u32_e32 v167, v122, v155
	ds_read_b128 v[168:171], v167
	ds_read_b128 v[172:175], v167 offset:4352
	ds_read_b128 v[176:179], v167 offset:8704
	ds_read_b128 v[240:243], v167 offset:13056
	ds_read_b128 v[244:247], v167 offset:64
	v_xor_b32_e32 v114, 0x80000000, v165
	v_xor_b32_e32 v118, 0x80000000, v164
	v_mov_b32_e32 v115, v114
	v_mov_b32_e32 v116, v114
	v_mov_b32_e32 v117, v114
	v_mov_b32_e32 v119, v118
	v_mov_b32_e32 v120, v118
	v_mov_b32_e32 v121, v118
	s_nop 1
	s_waitcnt lgkmcnt(4)
	v_mfma_f32_16x16x32_bf16 v[142:145], v[168:171], v[50:53], v[118:121]
	s_waitcnt lgkmcnt(3)
	v_mfma_f32_16x16x32_bf16 v[122:125], v[172:175], v[34:37], v[114:117]
	s_waitcnt lgkmcnt(2)
	v_mfma_f32_16x16x32_bf16 v[126:129], v[176:179], v[34:37], v[114:117]
	v_mfma_f32_16x16x32_bf16 v[134:137], v[176:179], v[50:53], v[118:121]
	ds_read_b128 v[176:179], v167 offset:4416
	s_waitcnt lgkmcnt(2)
	v_mfma_f32_16x16x32_bf16 v[130:133], v[240:243], v[34:37], v[114:117]
	v_mfma_f32_16x16x32_bf16 v[138:141], v[240:243], v[50:53], v[118:121]
	ds_read_b128 v[240:243], v167 offset:8768
	v_mfma_f32_16x16x32_bf16 v[114:117], v[168:171], v[34:37], v[114:117]
	ds_read_b128 v[168:171], v167 offset:13120
	v_mfma_f32_16x16x32_bf16 v[118:121], v[172:175], v[50:53], v[118:121]
	ds_read_b128 v[172:175], v167 offset:128
	s_waitcnt lgkmcnt(4)
	v_mfma_f32_16x16x32_bf16 v[114:117], v[244:247], v[38:41], v[114:117]
	v_mfma_f32_16x16x32_bf16 v[142:145], v[244:247], v[54:57], v[142:145]
	ds_read_b128 v[244:247], v167 offset:4480
	s_waitcnt lgkmcnt(4)
	v_mfma_f32_16x16x32_bf16 v[122:125], v[176:179], v[38:41], v[122:125]
	v_mfma_f32_16x16x32_bf16 v[118:121], v[176:179], v[54:57], v[118:121]
	ds_read_b128 v[176:179], v167 offset:8832
	s_waitcnt lgkmcnt(4)
	v_mfma_f32_16x16x32_bf16 v[126:129], v[240:243], v[38:41], v[126:129]
	v_mfma_f32_16x16x32_bf16 v[134:137], v[240:243], v[54:57], v[134:137]
	ds_read_b128 v[240:243], v167 offset:13184
	s_waitcnt lgkmcnt(4)
	v_mfma_f32_16x16x32_bf16 v[130:133], v[168:171], v[38:41], v[130:133]
	v_mfma_f32_16x16x32_bf16 v[138:141], v[168:171], v[54:57], v[138:141]
	ds_read_b128 v[168:171], v167 offset:192
	s_waitcnt lgkmcnt(4)
	v_mfma_f32_16x16x32_bf16 v[114:117], v[172:175], v[42:45], v[114:117]
	v_mfma_f32_16x16x32_bf16 v[142:145], v[172:175], v[58:61], v[142:145]
	ds_read_b128 v[172:175], v167 offset:4544
	s_waitcnt lgkmcnt(4)
	v_mfma_f32_16x16x32_bf16 v[122:125], v[244:247], v[42:45], v[122:125]
	v_mfma_f32_16x16x32_bf16 v[118:121], v[244:247], v[58:61], v[118:121]
	ds_read_b128 v[244:247], v167 offset:8896
	s_waitcnt lgkmcnt(4)
	v_mfma_f32_16x16x32_bf16 v[126:129], v[176:179], v[42:45], v[126:129]
	v_mfma_f32_16x16x32_bf16 v[134:137], v[176:179], v[58:61], v[134:137]
	ds_read_b128 v[176:179], v167 offset:13248
	s_waitcnt lgkmcnt(4)
	v_mfma_f32_16x16x32_bf16 v[130:133], v[240:243], v[42:45], v[130:133]
	v_mfma_f32_16x16x32_bf16 v[138:141], v[240:243], v[58:61], v[138:141]
	s_waitcnt lgkmcnt(3)
	v_mfma_f32_16x16x32_bf16 v[114:117], v[168:171], v[46:49], v[114:117]
	s_waitcnt lgkmcnt(2)
	v_mfma_f32_16x16x32_bf16 v[122:125], v[172:175], v[46:49], v[122:125]
	s_waitcnt lgkmcnt(1)
	v_mfma_f32_16x16x32_bf16 v[126:129], v[244:247], v[46:49], v[126:129]
	s_waitcnt lgkmcnt(0)
	v_mfma_f32_16x16x32_bf16 v[130:133], v[176:179], v[46:49], v[130:133]
	v_mfma_f32_16x16x32_bf16 v[142:145], v[168:171], v[62:65], v[142:145]
	v_mfma_f32_16x16x32_bf16 v[118:121], v[172:175], v[62:65], v[118:121]
	v_mfma_f32_16x16x32_bf16 v[134:137], v[244:247], v[62:65], v[134:137]
	v_mfma_f32_16x16x32_bf16 v[138:141], v[176:179], v[62:65], v[138:141]
	s_nop 0
	v_max_f32_e32 v167, v115, v115
	v_max_f32_e32 v168, v114, v114
	v_max_f32_e32 v167, v168, v167
	v_max_f32_e32 v168, v117, v117
	v_max_f32_e32 v169, v116, v116
	v_max_f32_e32 v168, v169, v168
	v_max_f32_e32 v169, v125, v125
	v_max_f32_e32 v170, v124, v124
	v_max_f32_e32 v169, v170, v169
	v_max3_f32 v169, v122, v123, v169
	v_max3_f32 v167, v167, v168, v169
	v_max_f32_e32 v168, v129, v129
	v_max_f32_e32 v169, v128, v128
	v_max_f32_e32 v168, v169, v168
	v_max_f32_e32 v169, v133, v133
	v_max_f32_e32 v170, v132, v132
	v_max_f32_e32 v169, v170, v169
	v_max3_f32 v168, v126, v127, v168
	v_max3_f32 v169, v130, v131, v169
	v_max3_f32 v167, v167, v168, v169
	v_mov_b32_e32 v168, v167
	s_nop 1
	v_permlane16_swap_b32_e32 v167, v168
	v_max_f32_e32 v168, v168, v168
	v_max_f32_e32 v167, v167, v167
	v_max_f32_e32 v167, v167, v168
	v_mov_b32_e32 v168, v167
	s_nop 1
	v_permlane32_swap_b32_e32 v167, v168
	v_max_f32_e32 v168, v168, v168
	v_max_f32_e32 v167, v167, v167
	v_max_f32_e32 v167, v167, v168
	v_cmp_lt_f32_e32 vcc, s5, v167
	s_cbranch_vccz .LBB0_829
	s_nop 0
	v_cndmask_b32_e32 v167, 0, v167, vcc
	v_exp_f32_e64 v168, -v167
	v_add_f32_e32 v165, v165, v167
	v_sub_f32_e32 v114, v114, v167
	v_sub_f32_e32 v115, v115, v167
	v_mul_f32_e32 v157, v157, v168
	v_sub_f32_e32 v116, v116, v167
	v_sub_f32_e32 v117, v117, v167
	v_sub_f32_e32 v122, v122, v167
	v_sub_f32_e32 v123, v123, v167
	v_sub_f32_e32 v124, v124, v167
	v_sub_f32_e32 v125, v125, v167
	v_sub_f32_e32 v126, v126, v167
	v_sub_f32_e32 v127, v127, v167
	v_sub_f32_e32 v128, v128, v167
	v_sub_f32_e32 v129, v129, v167
	v_sub_f32_e32 v130, v130, v167
	v_sub_f32_e32 v131, v131, v167
	v_sub_f32_e32 v132, v132, v167
	v_sub_f32_e32 v133, v133, v167
	v_pk_mul_f32 v[112:113], v[112:113], v[168:169] op_sel_hi:[1,0]
	v_pk_mul_f32 v[110:111], v[110:111], v[168:169] op_sel_hi:[1,0]
	v_pk_mul_f32 v[92:93], v[92:93], v[168:169] op_sel_hi:[1,0]
	v_pk_mul_f32 v[90:91], v[90:91], v[168:169] op_sel_hi:[1,0]
	v_pk_mul_f32 v[88:89], v[88:89], v[168:169] op_sel_hi:[1,0]
	v_pk_mul_f32 v[86:87], v[86:87], v[168:169] op_sel_hi:[1,0]
	v_pk_mul_f32 v[84:85], v[84:85], v[168:169] op_sel_hi:[1,0]
	v_pk_mul_f32 v[82:83], v[82:83], v[168:169] op_sel_hi:[1,0]
	v_pk_mul_f32 v[80:81], v[80:81], v[168:169] op_sel_hi:[1,0]
	v_pk_mul_f32 v[78:79], v[78:79], v[168:169] op_sel_hi:[1,0]
	v_pk_mul_f32 v[76:77], v[76:77], v[168:169] op_sel_hi:[1,0]
	v_pk_mul_f32 v[74:75], v[74:75], v[168:169] op_sel_hi:[1,0]
	v_pk_mul_f32 v[72:73], v[72:73], v[168:169] op_sel_hi:[1,0]
	v_pk_mul_f32 v[70:71], v[70:71], v[168:169] op_sel_hi:[1,0]
	v_pk_mul_f32 v[68:69], v[68:69], v[168:169] op_sel_hi:[1,0]
	v_pk_mul_f32 v[66:67], v[66:67], v[168:169] op_sel_hi:[1,0]
